# attention unit boundary: closing barrier moved to epilogue start, next virtual head's first K/V tiles (+Q when the map changes) requested there; tile-0 K fragment reads issued together
# baseline (speedup 1.0000x reference)
; __device__ __forceinline__ int crow(int r,int hi){return (r&3)+8*(r>>2)+4*hi;}
;   #define DMA_K(t,slot) glds16(ksrc+(long)(t)*KVBLK*PQ,(unsigned)__builtin_amdgcn_readfirstlane(kdst+(slot)))
;   #define DMA_V(t,slot) glds16(vsrc+(long)(t)*KVBLK*PQ,(unsigned)__builtin_amdgcn_readfirstlane(vdst+(slot)))
; template<int THRL> __device__ __forceinline__ void attn_unit(int b,int qb,const bf16*Q,const bf16*__restrict__ K,const bf16*__restrict__ V,bf16*O,const __attribute__((address_space(3))) float*tab,char*shm){
;     ...
;   const bf16*Qw=Q+(rowbase+q0+wid*QBLK)*PQ;
;   const bf16*Kh=K+rowbase*PQ,*Vh=V+rowbase*PQ;
;   const unsigned lds0=(unsigned)(uintptr_t)shm;
;   float*wsf=(float*)(shm+LDS_WS)+wid*64;
;   const bf16*ksrc=Kh+(long)lane*PQ+wid*8;
;   const bf16*vsrc=Vh+(long)(16*(wid&3)+(lane>>2))*PQ+(wid>>2)*32+(lane&3)*8;
;   const unsigned kdst=lds0+LDS_K+wid*1024, vdst=lds0+LDS_V+wid*1024;
;     ...
;   const int vb0=(int)(lds0+LDS_V)+((lane>>4)&1)*32+(lane&3)*8+(4*hi+((lane&15)>>2))*64;
;   const char*Kbase=shm+LDS_K; bf16x8 kf[8];
;   const lds_cptr shm3=(lds_cptr)shm; const lds_cptr kp0=shm3+LDS_K+hi*1024+r32*16; const lds_cptr vp0=shm3+LDS_V+((lane>>4)&1)*32+(lane&3)*8+(4*hi+((lane&15)>>2))*64;
;   const int NT=(q0+QB)/KVBLK;
;   DMA_K(0,0);DMA_V(0,0);DMA_K(1,SLOTB);
;   bf16x8 qr[4];
;   #pragma unroll
;   for(int d0=0;d0<4;++d0)qr[d0]=*reinterpret_cast<const bf16x8*>(&Qw[(long)r32*PQ+d0*16+hi*8]);
;     ...
;   {auto rr=__builtin_amdgcn_permlane32_swap(__float_as_uint(l_reg),__float_as_uint(l_reg),false,false);l_reg=__uint_as_float(rr[0])+__uint_as_float(rr[1]);}
;   if(hi==0)wsf[32+r32]=l_reg;asm volatile("s_waitcnt lgkmcnt(0)":::"memory");
;   float rli[16];
;   #pragma unroll
;   for(int r=0;r<16;++r)rli[r]=__builtin_amdgcn_rcpf(wsf[32+crow(r,hi)]);
;   bf16*Ow=O+(rowbase+q0+wid*QBLK)*PO;
;   { bf16*stg=(bf16*)(shm+LDS_OST)+wid*2048;
;     #pragma unroll
;     for(int r=0;r<16;++r){const int orow=crow(r,hi);
;       #pragma unroll
;       for(int d0=0;d0<2;++d0)stg[orow*64+d0*32+r32]=__float2bfloat16(o[d0][r]*rli[r]);}
;     asm volatile("s_waitcnt lgkmcnt(0)":::"memory");
;     #pragma unroll
;     for(int i=0;i<4;++i){const int row=i*8+(lane>>3),ch=lane&7; const u32x4 v=*(const u32x4*)(stg+row*64+ch*8); ATTN_STORE16(Ow+(long)row*PO+ch*8,v);} }
;   asm volatile("s_waitcnt lgkmcnt(0)\n\ts_barrier":::"memory");
.LBB0_370:
	s_or_b64 exec, exec, s[6:7]
	s_waitcnt lgkmcnt(0)
	s_barrier
	s_cmp_eq_u32 s46, 3
	s_cbranch_scc1 .Lpf_none
	s_add_i32 s6, s46, 1
	s_lshr_b32 s7, s6, 1
	s_lshl_b32 s7, s7, 7
	s_and_b32 s6, s6, 1
	s_lshl_b32 s6, s6, 7
	s_add_u32 s8, s69, s7
	s_addc_u32 s9, s49, 0
	v_lshlrev_b32_e32 v160, 12, v220
	v_mov_b32_e32 v161, 0
	v_lshl_add_u64 v[160:161], s[8:9], 0, v[160:161]
	s_lshl_b32 s8, s26, 4
	s_mov_b32 s9, 0
	v_lshl_add_u64 v[160:161], v[160:161], 0, s[8:9]
	s_add_u32 s8, s55, s6
	s_addc_u32 s9, s45, 0
	v_bfe_u32 v162, v206, 2, 4
	s_lshl_b32 s6, s26, 4
	v_and_or_b32 v162, s6, 48, v162
	v_lshlrev_b32_e32 v162, 12, v162
	v_mov_b32_e32 v163, 0
	v_lshl_add_u64 v[162:163], s[8:9], 0, v[162:163]
	s_lshr_b32 s6, s26, 2
	s_lshl_b32 s6, s6, 6
	s_mov_b32 s7, 0
	v_lshl_add_u64 v[162:163], v[162:163], 0, s[6:7]
	v_and_b32_e32 v164, 3, v206
	v_lshlrev_b32_e32 v164, 4, v164
	v_mov_b32_e32 v165, 0
	v_lshl_add_u64 v[162:163], v[162:163], 0, v[164:165]
	v_lshl_add_u64 v[164:165], v[160:161], 0, s[22:23]
	v_lshl_add_u64 v[166:167], v[160:161], 0, s[34:35]
	s_mov_b32 s12, m0
	s_mov_b32 m0, s97
	s_nop 0
	global_load_lds_dwordx4 v[160:161], off
	s_cmp_lg_u32 s46, 1
	s_cbranch_scc1 .Lpf_noq
	s_lshl_b64 s[8:9], s[82:83], 12
	s_add_u32 s8, s8, s14
	s_addc_u32 s9, s9, s15
	s_add_u32 s8, s8, 0x80
	s_addc_u32 s9, s9, 0
	v_lshlrev_b32_e32 v168, 12, v222
	v_lshl_or_b32 v168, v223, 4, v168
	global_load_dwordx4 v[156:159], v168, s[8:9]
	global_load_dwordx4 v[152:155], v168, s[8:9] offset:32
	global_load_dwordx4 v[148:151], v168, s[8:9] offset:64
	global_load_dwordx4 v[144:147], v168, s[8:9] offset:96
.Lpf_noq:
	s_mov_b32 m0, s95
	s_nop 0
	global_load_lds_dwordx4 v[162:163], off
	s_add_i32 s6, s97, 0x2000
	s_mov_b32 m0, s6
	s_nop 0
	global_load_lds_dwordx4 v[164:165], off
	s_add_i32 s6, s97, 0x4000
	s_mov_b32 m0, s6
	s_nop 0
	global_load_lds_dwordx4 v[166:167], off
	s_mov_b32 m0, s12
.Lpf_none:
	ds_read_b128 v[4:7], v2 offset:49280
	ds_read_b128 v[8:11], v2 offset:49312
	s_lshl_b32 s6, s27, 10
	s_add_u32 s6, s54, s6
	s_addc_u32 s7, s68, 0
	s_waitcnt lgkmcnt(1)
	v_rcp_f32_e32 v0, v4
	v_rcp_f32_e32 v3, v5
	v_rcp_f32_e32 v12, v6
	v_rcp_f32_e32 v13, v7
	s_waitcnt lgkmcnt(0)
	v_rcp_f32_e32 v14, v8
	ds_read_b128 v[4:7], v2 offset:49344
	v_rcp_f32_e32 v15, v9
	v_rcp_f32_e32 v48, v10
	v_rcp_f32_e32 v49, v11
	ds_read_b128 v[8:11], v2 offset:49376
	s_add_u32 s8, s6, s28
	s_addc_u32 s9, s7, 0
	s_lshl_b32 s12, s26, 12
	s_waitcnt lgkmcnt(1)
	v_rcp_f32_e32 v2, v4
	v_rcp_f32_e32 v4, v5
	v_rcp_f32_e32 v5, v6
	v_rcp_f32_e32 v6, v7
	s_waitcnt lgkmcnt(0)
	v_rcp_f32_e32 v7, v8
	v_rcp_f32_e32 v8, v9
	v_rcp_f32_e32 v9, v10
	v_rcp_f32_e32 v10, v11
	s_add_i32 s12, s12, 0
	v_lshlrev_b32_e32 v11, 1, v222
	v_lshlrev_b32_e32 v50, 9, v223
	v_mul_f32_e32 v32, v32, v0
	v_mul_f32_e32 v0, v16, v0
	v_add3_u32 v11, s12, v11, v50
	v_cvt_pk_bf16_f32 v0, v0, s0
	ds_write_b16 v11, v0 offset:54336
	v_mul_f32_e32 v0, v33, v3
	v_cvt_pk_bf16_f32 v0, v0, s0
	ds_write_b16 v11, v0 offset:54400
	v_mul_f32_e32 v0, v17, v3
	v_cvt_pk_bf16_f32 v0, v0, s0
	ds_write_b16 v11, v0 offset:54464
	v_mul_f32_e32 v0, v34, v12
	v_cvt_pk_bf16_f32 v0, v0, s0
	ds_write_b16 v11, v0 offset:54528
	v_mul_f32_e32 v0, v18, v12
	v_cvt_pk_bf16_f32 v0, v0, s0
	ds_write_b16 v11, v0 offset:54592
	v_mul_f32_e32 v0, v35, v13
	v_cvt_pk_bf16_f32 v0, v0, s0
	ds_write_b16 v11, v0 offset:54656
	v_mul_f32_e32 v0, v19, v13
	v_cvt_pk_bf16_f32 v0, v0, s0
	ds_write_b16 v11, v0 offset:54720
	v_mul_f32_e32 v0, v36, v14
	v_cvt_pk_bf16_f32 v0, v0, s0
	ds_write_b16 v11, v0 offset:55296
	v_mul_f32_e32 v0, v20, v14
	v_cvt_pk_bf16_f32 v0, v0, s0
	ds_write_b16 v11, v0 offset:55360
	v_mul_f32_e32 v0, v37, v15
	v_cvt_pk_bf16_f32 v0, v0, s0
	ds_write_b16 v11, v0 offset:55424
	v_mul_f32_e32 v0, v21, v15
	v_cvt_pk_bf16_f32 v0, v0, s0
	ds_write_b16 v11, v0 offset:55488
	v_mul_f32_e32 v0, v38, v48
	v_cvt_pk_bf16_f32 v0, v0, s0
	ds_write_b16 v11, v0 offset:55552
	v_mul_f32_e32 v0, v22, v48
	v_cvt_pk_bf16_f32 v0, v0, s0
	ds_write_b16 v11, v0 offset:55616
	v_mul_f32_e32 v0, v39, v49
	v_cvt_pk_bf16_f32 v0, v0, s0
	ds_write_b16 v11, v0 offset:55680
	v_mul_f32_e32 v0, v23, v49
	v_cvt_pk_bf16_f32 v0, v0, s0
	ds_write_b16 v11, v0 offset:55744
	v_mul_f32_e32 v0, v40, v2
	v_cvt_pk_bf16_f32 v0, v0, s0
	ds_write_b16 v11, v0 offset:56320
	v_mul_f32_e32 v0, v24, v2
	v_cvt_pk_bf16_f32 v0, v0, s0
	ds_write_b16 v11, v0 offset:56384
	v_mul_f32_e32 v0, v41, v4
	v_cvt_pk_bf16_f32 v0, v0, s0
	ds_write_b16 v11, v0 offset:56448
	v_mul_f32_e32 v0, v25, v4
	v_cvt_pk_bf16_f32 v0, v0, s0
	ds_write_b16 v11, v0 offset:56512
	v_mul_f32_e32 v0, v42, v5
	v_cvt_pk_bf16_f32 v0, v0, s0
	ds_write_b16 v11, v0 offset:56576
	v_mul_f32_e32 v0, v26, v5
	v_cvt_pk_bf16_f32 v0, v0, s0
	ds_write_b16 v11, v0 offset:56640
	v_mul_f32_e32 v0, v43, v6
	v_cvt_pk_bf16_f32 v0, v0, s0
	ds_write_b16 v11, v0 offset:56704
	v_mul_f32_e32 v0, v27, v6
	v_cvt_pk_bf16_f32 v0, v0, s0
	ds_write_b16 v11, v0 offset:56768
	v_mul_f32_e32 v0, v44, v7
	v_cvt_pk_bf16_f32 v0, v0, s0
	ds_write_b16 v11, v0 offset:57344
	v_mul_f32_e32 v0, v28, v7
	v_cvt_pk_bf16_f32 v0, v0, s0
	ds_write_b16 v11, v0 offset:57408
	v_mul_f32_e32 v0, v45, v8
	v_cvt_pk_bf16_f32 v0, v0, s0
	ds_write_b16 v11, v0 offset:57472
	v_mul_f32_e32 v0, v29, v8
	v_cvt_pk_bf16_f32 v0, v0, s0
	ds_write_b16 v11, v0 offset:57536
	v_mul_f32_e32 v0, v46, v9
	v_cvt_pk_bf16_f32 v0, v0, s0
	ds_write_b16 v11, v0 offset:57600
	v_mul_f32_e32 v0, v30, v9
	v_cvt_pk_bf16_f32 v0, v0, s0
	ds_write_b16 v11, v0 offset:57664
	v_mul_f32_e32 v0, v47, v10
	v_cvt_pk_bf16_f32 v0, v0, s0
	ds_write_b16 v11, v0 offset:57728
	v_mul_f32_e32 v0, v31, v10
	v_cvt_pk_bf16_f32 v0, v0, s0
	s_lshl_b64 s[6:7], s[82:83], 11
	ds_write_b16 v11, v0 offset:57792
	v_lshlrev_b32_e32 v0, 1, v221
	v_cvt_pk_bf16_f32 v32, v32, s0
	s_add_u32 s6, s8, s6
	v_and_b32_e32 v0, 0x70, v0
	ds_write_b16 v11, v32 offset:54272
	s_addc_u32 s7, s9, s7
	v_lshrrev_b32_e32 v14, 3, v220
	v_add_u32_e32 v15, s12, v0
	s_waitcnt lgkmcnt(0)
	v_lshl_add_u64 v[10:11], s[6:7], 0, v[0:1]
	v_lshl_add_u32 v0, v14, 7, v15
	v_or_b32_e32 v16, 8, v14
	ds_read_b128 v[2:5], v0 offset:54272
	v_lshl_add_u32 v6, v16, 7, v15
	ds_read_b128 v[6:9], v6 offset:54272
	v_lshlrev_b32_e32 v0, 11, v14
	v_lshl_add_u64 v[12:13], v[10:11], 0, v[0:1]
	v_lshlrev_b32_e32 v0, 11, v16
	s_waitcnt lgkmcnt(1)
	global_store_dwordx4 v[12:13], v[2:5], off
	s_add_i32 s46, s46, 1
	s_cmp_eq_u32 s46, 4
	v_lshl_add_u64 v[2:3], v[10:11], 0, v[0:1]
	v_or_b32_e32 v0, 16, v14
	s_waitcnt lgkmcnt(0)
	global_store_dwordx4 v[2:3], v[6:9], off
	v_lshl_add_u32 v2, v0, 7, v15
	v_or_b32_e32 v14, 24, v14
	ds_read_b128 v[2:5], v2 offset:54272
	v_lshl_add_u32 v6, v14, 7, v15
	ds_read_b128 v[6:9], v6 offset:54272
	v_lshlrev_b32_e32 v0, 11, v0
	v_lshl_add_u64 v[12:13], v[10:11], 0, v[0:1]
	v_lshlrev_b32_e32 v0, 11, v14
	s_waitcnt lgkmcnt(1)
	global_store_dwordx4 v[12:13], v[2:5], off
	s_nop 1
	v_lshl_add_u64 v[2:3], v[10:11], 0, v[0:1]
	s_waitcnt lgkmcnt(0)
	global_store_dwordx4 v[2:3], v[6:9], off
	s_waitcnt lgkmcnt(0)
	s_cbranch_scc0 .Lpf_more
;   #define DMA_K(t,slot) glds16(ksrc+(long)(t)*KVBLK*PQ,(unsigned)__builtin_amdgcn_readfirstlane(kdst+(slot)))
;   #define DMA_V(t,slot) glds16(vsrc+(long)(t)*KVBLK*PQ,(unsigned)__builtin_amdgcn_readfirstlane(vdst+(slot)))
; template<int THRL> __device__ __forceinline__ void attn_unit(int b,int qb,const bf16*Q,const bf16*__restrict__ K,const bf16*__restrict__ V,bf16*O,const __attribute__((address_space(3))) float*tab,char*shm){
;   int tid_=threadIdx.x; asm volatile("":"+v"(tid_)); const int tid=tid_,lane=tid&63,r32=lane&31,hi=lane>>5; const int wid=__builtin_amdgcn_readfirstlane(tid>>6);
;   const long rowbase=(long)b*SEQ; const int q0=qb*QB;
;   const bf16*Qw=Q+(rowbase+q0+wid*QBLK)*PQ;
;   const bf16*Kh=K+rowbase*PQ,*Vh=V+rowbase*PQ;
;   const unsigned lds0=(unsigned)(uintptr_t)shm;
;   float*wsf=(float*)(shm+LDS_WS)+wid*64;
;   const bf16*ksrc=Kh+(long)lane*PQ+wid*8;
;   const bf16*vsrc=Vh+(long)(16*(wid&3)+(lane>>2))*PQ+(wid>>2)*32+(lane&3)*8;
;   const unsigned kdst=lds0+LDS_K+wid*1024, vdst=lds0+LDS_V+wid*1024;
;     ...
;   const int vb0=(int)(lds0+LDS_V)+((lane>>4)&1)*32+(lane&3)*8+(4*hi+((lane&15)>>2))*64;
;   const char*Kbase=shm+LDS_K; bf16x8 kf[8];
;   const lds_cptr shm3=(lds_cptr)shm; const lds_cptr kp0=shm3+LDS_K+hi*1024+r32*16; const lds_cptr vp0=shm3+LDS_V+((lane>>4)&1)*32+(lane&3)*8+(4*hi+((lane&15)>>2))*64;
;   const int NT=(q0+QB)/KVBLK;
;   DMA_K(0,0);DMA_V(0,0);DMA_K(1,SLOTB);
;   bf16x8 qr[4];
;   #pragma unroll
;   for(int d0=0;d0<4;++d0)qr[d0]=*reinterpret_cast<const bf16x8*>(&Qw[(long)r32*PQ+d0*16+hi*8]);
; __global__ void __launch_bounds__(NWAVES * 64, 2) trunk_fwd(Args args) {
;     ...
;                     for (int vh = 0; vh < 4; ++vh) { const int mp = vh >> 1, j = vh & 1;
;     ...
;                         attn_body::attn_unit<8>(b, qb, (const attn_body::bf16*)(BIG + h * 128 + mp * 64), (const attn_body::bf16*)(BIG + 512 + h * 128 + mp * 64), (const attn_body::bf16*)(BIG + 1024 + h * 128 + j * 64),
;                                                 (attn_body::bf16*)(ORAW + mp * 512 + h * 128 + j * 64), tab, (char*)lds);
;     ...
;                         asm volatile("s_waitcnt vmcnt(0)" ::: "memory");
	s_waitcnt vmcnt(0)
	s_branch .LBB0_363
.Lpf_more:
	s_waitcnt vmcnt(7)
.LBB0_371:
	s_lshr_b32 s27, s46, 1
	s_lshl_b32 s6, s27, 7
	s_add_u32 s12, s14, s6
	s_addc_u32 s28, s15, 0
	s_lshl_b32 s7, s46, 6
	s_cmp_lg_u32 s46, 0
	s_cbranch_scc1 .Lpf_nowait
	s_waitcnt vmcnt(0)
.Lpf_nowait:
	v_mov_b32_e32 v34, v206
	s_and_b32 s29, s7, 64
	v_mov_b32_e32 v4, v1
	v_readfirstlane_b32 s7, v34
	s_ashr_i32 s26, s7, 6
	s_lshl_b32 s88, s26, 5
	s_ashr_i32 s8, s88, 31
	s_add_u32 s82, s43, s88
	s_addc_u32 s83, s44, s8
	s_lshl_b64 s[8:9], s[82:83], 12
	s_add_u32 s8, s12, s8
	s_addc_u32 s9, s28, s9
	s_add_u32 s84, s69, s6
	v_and_b32_e32 v220, 63, v34
	s_addc_u32 s85, s49, 0
	s_lshl_b32 s28, s29, 1
	s_add_u32 s86, s55, s28
	v_lshlrev_b32_e32 v0, 12, v220
	s_addc_u32 s87, s45, 0
	s_waitcnt lgkmcnt(0)
	v_lshl_add_u64 v[2:3], s[84:85], 0, v[0:1]
	s_lshl_b32 s84, s26, 3
	s_lshl_b32 s6, s26, 4
	v_bfe_u32 v0, v34, 2, 4
	s_ashr_i32 s85, s84, 31
	v_and_or_b32 v0, s6, 48, v0
	s_ashr_i32 s6, s7, 3
	v_lshl_add_u64 v[204:205], s[84:85], 1, v[2:3]
	s_and_b32 s84, s6, 0xffffffe0
	s_ashr_i32 s85, s84, 31
	s_lshl_b32 s6, s26, 10
	v_lshlrev_b32_e32 v0, 12, v0
	v_lshlrev_b32_e32 v221, 3, v34
	s_cmp_lg_u32 0, -1
	v_lshl_add_u64 v[2:3], s[86:87], 0, v[0:1]
	v_and_b32_e32 v224, 24, v221
	s_cselect_b32 s12, 0, 0
	v_and_b32_e32 v222, 31, v34
	v_lshl_add_u64 v[2:3], s[84:85], 1, v[2:3]
	v_lshlrev_b32_e32 v0, 1, v224
	s_add_i32 s97, s6, s12
	v_bfe_u32 v223, v34, 5, 1
	v_lshl_add_u64 v[212:213], v[2:3], 0, v[0:1]
	s_add_i32 s95, s97, 0x6000
	v_lshlrev_b32_e32 v0, 12, v222
	v_lshl_add_u64 v[2:3], v[204:205], 0, s[22:23]
	s_add_i32 s12, s97, 0x2000
	v_lshl_or_b32 v0, v223, 4, v0
	s_cmp_lg_u32 s46, 0
	s_cbranch_scc1 .Lpf_pro1
	s_mov_b32 s29, m0
	s_mov_b32 m0, s97
	s_nop 0
	global_load_lds_dwordx4 v[204:205], off
	s_mov_b32 m0, s95
	s_nop 0
	global_load_lds_dwordx4 v[212:213], off
	s_mov_b32 m0, s12
	s_nop 0
	global_load_lds_dwordx4 v[2:3], off
	s_mov_b32 m0, s29
	global_load_dwordx4 v[156:159], v0, s[8:9]
	global_load_dwordx4 v[152:155], v0, s[8:9] offset:32
	global_load_dwordx4 v[148:151], v0, s[8:9] offset:64
	global_load_dwordx4 v[144:147], v0, s[8:9] offset:96
.Lpf_pro1:
	v_mov_b32_e32 v2, v1
	v_mov_b32_e32 v3, v1
	v_mov_b32_e32 v5, v1
	v_mov_b32_e32 v6, v1
	v_mov_b32_e32 v7, v1
	v_mov_b32_e32 v8, v1
	v_mov_b32_e32 v9, v1
	v_mov_b32_e32 v10, v1
	v_mov_b32_e32 v11, v1
	v_mov_b32_e32 v12, v1
	v_mov_b32_e32 v13, v1
	v_mov_b32_e32 v14, v1
	v_mov_b32_e32 v15, v1
	v_lshlrev_b32_e32 v0, 10, v223
	v_lshlrev_b32_e32 v16, 4, v222
	v_add3_u32 v231, 0, v0, v16
	v_mov_b32_e32 v0, v1
	v_mov_b64_e32 v[16:17], v[14:15]
	v_mov_b64_e32 v[14:15], v[12:13]
	v_mov_b64_e32 v[12:13], v[10:11]
	v_mov_b64_e32 v[10:11], v[8:9]
	v_mov_b64_e32 v[8:9], v[6:7]
	v_mov_b64_e32 v[6:7], v[4:5]
	v_mov_b64_e32 v[4:5], v[2:3]
	v_mov_b64_e32 v[2:3], v[0:1]
	v_lshl_add_u64 v[18:19], v[204:205], 0, s[34:35]
	s_add_i32 s8, s97, 0x4000
	s_cmp_lg_u32 s46, 0
	s_cbranch_scc1 .Lpf_tile0
	s_mov_b32 s9, m0
	s_mov_b32 m0, s8
	s_nop 0
	global_load_lds_dwordx4 v[18:19], off
	s_mov_b32 m0, s9
	s_waitcnt vmcnt(3) lgkmcnt(0)
	s_barrier

; #define WAIT_BAR(N) asm volatile("s_waitcnt vmcnt(" #N ") lgkmcnt(0)\n\ts_barrier":::"memory")
;   #define DMA_K(t,slot) glds16(ksrc+(long)(t)*KVBLK*PQ,(unsigned)__builtin_amdgcn_readfirstlane(kdst+(slot)))
;   #define CMASK(P0,P1,t) do{int jb_=(t)-(NT-4); if(jb_>=-2)cmask(P0,P1,jb_,qrel,hi,tab);}while(0)
;   #define CMASK(P0,P1,t) do{}while(0)
;   #define CMASK(P0,P1,t) do{int jb_=(t)-(NT-4); if(jb_>=-2)cmask(P0,P1,jb_,qrel,hi,tab);}while(0)
; __device__ __forceinline__ void qkt(f32x16&p0,f32x16&p1,const char*Kslot,const bf16x8*qr,const f32x16&negm,int r32,int hi){
;   const char*kb=Kslot+hi*1024+r32*16;
;   #pragma unroll
;   for(int d0=0;d0<4;++d0){
;     const bf16x8 b0=*reinterpret_cast<const bf16x8*>(kb+d0*2048);
;     const bf16x8 b1=*reinterpret_cast<const bf16x8*>(kb+d0*2048+512);
;     if(d0==0){p0=__builtin_amdgcn_mfma_f32_32x32x16_bf16(b0,qr[0],negm,0,0,0);p1=__builtin_amdgcn_mfma_f32_32x32x16_bf16(b1,qr[0],negm,0,0,0);}
;     else{p0=__builtin_amdgcn_mfma_f32_32x32x16_bf16(b0,qr[d0],p0,0,0,0);p1=__builtin_amdgcn_mfma_f32_32x32x16_bf16(b1,qr[d0],p1,0,0,0);}}
; }
; template<int THRL> __device__ __forceinline__ void attn_unit(int b,int qb,const bf16*Q,const bf16*__restrict__ K,const bf16*__restrict__ V,bf16*O,const __attribute__((address_space(3))) float*tab,char*shm){
;     ...
;   DMA_K(2,2*SLOTB);
;   WAIT_BAR(3);
;   qkt(pA0,pA1,Kbase,qr,negm,r32,hi);asm volatile("s_nop 15\n\ts_nop 7":"+v"(pA0),"+v"(pA1));CMASK(pA0,pA1,0);
	ds_read_b128 v[188:191], v231
	ds_read_b128 v[184:187], v231 offset:512
	ds_read_b128 v[180:183], v231 offset:2048
	ds_read_b128 v[176:179], v231 offset:2560
	ds_read_b128 v[172:175], v231 offset:4096
	ds_read_b128 v[168:171], v231 offset:4608
	ds_read_b128 v[164:167], v231 offset:6144
	ds_read_b128 v[160:163], v231 offset:6656
	v_lshlrev_b32_e32 v225, 2, v223
	v_or_b32_e32 v0, s88, v222
	s_andn2_b64 vcc, exec, s[78:79]
	v_sub_u32_e32 v230, v0, v225
	s_waitcnt vmcnt(3) lgkmcnt(7)
	v_mfma_f32_32x32x16_bf16 v[18:33], v[188:191], v[156:159], v[2:17]
	s_waitcnt lgkmcnt(6)
	v_mfma_f32_32x32x16_bf16 v[2:17], v[184:187], v[156:159], v[2:17]
	s_waitcnt vmcnt(2) lgkmcnt(5)
	v_mfma_f32_32x32x16_bf16 v[18:33], v[180:183], v[152:155], v[18:33]
	s_waitcnt lgkmcnt(4)
	v_mfma_f32_32x32x16_bf16 v[2:17], v[176:179], v[152:155], v[2:17]
	s_waitcnt vmcnt(1) lgkmcnt(3)
	v_mfma_f32_32x32x16_bf16 v[18:33], v[172:175], v[148:151], v[18:33]
	s_waitcnt lgkmcnt(2)
	v_mfma_f32_32x32x16_bf16 v[2:17], v[168:171], v[148:151], v[2:17]
	s_waitcnt vmcnt(0) lgkmcnt(1)
	v_mfma_f32_32x32x16_bf16 v[18:33], v[164:167], v[144:147], v[18:33]
	s_waitcnt lgkmcnt(0)
	v_mfma_f32_32x32x16_bf16 v[2:17], v[160:163], v[144:147], v[2:17]
	s_branch .Lpf_join
.Lpf_tile0:
	s_waitcnt lgkmcnt(0)
	s_barrier

; __device__ __forceinline__ void cmask(f32x16&p0,f32x16&p1,int jb,int qrel,int hi,const __attribute__((address_space(3))) float*tab){
;   asm volatile("s_nop 15\n\ts_nop 7":"+v"(p0),"+v"(p1));
;   const __attribute__((address_space(3))) float*tp=tab+(qrel-64*jb-4*hi+256);
;   #pragma unroll
;   for(int r=0;r<16;++r){const int o=(r&3)+8*(r>>2); float a0=tp[-o], a1=tp[-o-32]; asm volatile("v_add_f32_e32 %0, %1, %0":"+v"(p0[r]):"v"(a0)); asm volatile("v_add_f32_e32 %0, %1, %0":"+v"(p1[r]):"v"(a1));}
; }
; __device__ __forceinline__ void qkt(f32x16&p0,f32x16&p1,const char*Kslot,const bf16x8*qr,const f32x16&negm,int r32,int hi){
;   const char*kb=Kslot+hi*1024+r32*16;
;   #pragma unroll
;   for(int d0=0;d0<4;++d0){
;     const bf16x8 b0=*reinterpret_cast<const bf16x8*>(kb+d0*2048);
;     const bf16x8 b1=*reinterpret_cast<const bf16x8*>(kb+d0*2048+512);
;     if(d0==0){p0=__builtin_amdgcn_mfma_f32_32x32x16_bf16(b0,qr[0],negm,0,0,0);p1=__builtin_amdgcn_mfma_f32_32x32x16_bf16(b1,qr[0],negm,0,0,0);}
;     else{p0=__builtin_amdgcn_mfma_f32_32x32x16_bf16(b0,qr[d0],p0,0,0,0);p1=__builtin_amdgcn_mfma_f32_32x32x16_bf16(b1,qr[d0],p1,0,0,0);}}
; }
	ds_read_b128 v[188:191], v231
	ds_read_b128 v[184:187], v231 offset:512
	ds_read_b128 v[180:183], v231 offset:2048
	ds_read_b128 v[176:179], v231 offset:2560
	ds_read_b128 v[172:175], v231 offset:4096
	ds_read_b128 v[168:171], v231 offset:4608
	ds_read_b128 v[164:167], v231 offset:6144
	ds_read_b128 v[160:163], v231 offset:6656
	v_lshlrev_b32_e32 v225, 2, v223
	v_or_b32_e32 v0, s88, v222
	s_andn2_b64 vcc, exec, s[78:79]
	v_sub_u32_e32 v230, v0, v225
	s_waitcnt lgkmcnt(7)
	v_mfma_f32_32x32x16_bf16 v[18:33], v[188:191], v[156:159], v[2:17]
	s_waitcnt lgkmcnt(6)
	v_mfma_f32_32x32x16_bf16 v[2:17], v[184:187], v[156:159], v[2:17]
	s_waitcnt lgkmcnt(5)
	v_mfma_f32_32x32x16_bf16 v[18:33], v[180:183], v[152:155], v[18:33]
	s_waitcnt lgkmcnt(4)
	v_mfma_f32_32x32x16_bf16 v[2:17], v[176:179], v[152:155], v[2:17]
	s_waitcnt lgkmcnt(3)
	v_mfma_f32_32x32x16_bf16 v[18:33], v[172:175], v[148:151], v[18:33]
	s_waitcnt lgkmcnt(2)
	v_mfma_f32_32x32x16_bf16 v[2:17], v[168:171], v[148:151], v[2:17]
	s_waitcnt lgkmcnt(1)
	v_mfma_f32_32x32x16_bf16 v[18:33], v[164:167], v[144:147], v[18:33]
	s_waitcnt lgkmcnt(0)
	v_mfma_f32_32x32x16_bf16 v[2:17], v[160:163], v[144:147], v[2:17]
.Lpf_join:
	s_nop 15
	s_nop 7
	s_cbranch_vccnz .LBB0_373
	v_lshl_add_u32 v0, v230, 2, 0
	v_add_u32_e32 v35, 0xca00, v0
	s_nop 15
	s_nop 7
	ds_read2_b32 v[36:37], v35 offset0:96 offset1:128
	v_add_u32_e32 v0, 0xc800, v0
	s_waitcnt lgkmcnt(0)
	v_add_f32_e32 v18, v37, v18
	v_add_f32_e32 v2, v36, v2
	ds_read2_b32 v[36:37], v0 offset0:223 offset1:255
	s_waitcnt lgkmcnt(0)
	v_add_f32_e32 v19, v37, v19
	v_add_f32_e32 v3, v36, v3
	ds_read2_b32 v[36:37], v0 offset0:222 offset1:254
	s_waitcnt lgkmcnt(0)
	v_add_f32_e32 v20, v37, v20
	v_add_f32_e32 v4, v36, v4
	ds_read2_b32 v[36:37], v0 offset0:221 offset1:253
	s_waitcnt lgkmcnt(0)
	v_add_f32_e32 v21, v37, v21
	v_add_f32_e32 v5, v36, v5
	ds_read2_b32 v[36:37], v0 offset0:216 offset1:248
	s_waitcnt lgkmcnt(0)
	v_add_f32_e32 v22, v37, v22
	v_add_f32_e32 v6, v36, v6
	ds_read2_b32 v[36:37], v0 offset0:215 offset1:247
	s_waitcnt lgkmcnt(0)
	v_add_f32_e32 v23, v37, v23
	v_add_f32_e32 v7, v36, v7
	ds_read2_b32 v[36:37], v0 offset0:214 offset1:246
	s_waitcnt lgkmcnt(0)
	v_add_f32_e32 v24, v37, v24
	v_add_f32_e32 v8, v36, v8
	ds_read2_b32 v[36:37], v0 offset0:213 offset1:245
	s_waitcnt lgkmcnt(0)
	v_add_f32_e32 v25, v37, v25
	v_add_f32_e32 v9, v36, v9
	ds_read2_b32 v[36:37], v0 offset0:208 offset1:240
	s_waitcnt lgkmcnt(0)
	v_add_f32_e32 v26, v37, v26
	v_add_f32_e32 v10, v36, v10
	ds_read2_b32 v[36:37], v0 offset0:207 offset1:239
	s_waitcnt lgkmcnt(0)
	v_add_f32_e32 v27, v37, v27
	v_add_f32_e32 v11, v36, v11
	ds_read2_b32 v[36:37], v0 offset0:206 offset1:238
	s_waitcnt lgkmcnt(0)
	v_add_f32_e32 v28, v37, v28
	v_add_f32_e32 v12, v36, v12
	ds_read2_b32 v[36:37], v0 offset0:205 offset1:237
	s_waitcnt lgkmcnt(0)
	v_add_f32_e32 v29, v37, v29
	v_add_f32_e32 v13, v36, v13
	ds_read2_b32 v[36:37], v0 offset0:200 offset1:232
	s_waitcnt lgkmcnt(0)
	v_add_f32_e32 v30, v37, v30
	v_add_f32_e32 v14, v36, v14
	ds_read2_b32 v[36:37], v0 offset0:199 offset1:231
	s_waitcnt lgkmcnt(0)
	v_add_f32_e32 v31, v37, v31
	v_add_f32_e32 v15, v36, v15
	ds_read2_b32 v[36:37], v0 offset0:198 offset1:230
	s_waitcnt lgkmcnt(0)
	v_add_f32_e32 v32, v37, v32
	v_add_f32_e32 v16, v36, v16
	ds_read2_b32 v[36:37], v0 offset0:197 offset1:229
	s_waitcnt lgkmcnt(0)
	v_add_f32_e32 v33, v37, v33
	v_add_f32_e32 v17, v36, v17
